# stacked + GEMM2-phase param loads issued together (load_params ladder of 3 round trips -> 1)
# baseline (speedup 1.0000x reference)
.LBB0_456:
	s_or_b64 exec, exec, s[22:23]
	s_mov_b64 s[18:19], s[94:95]
	s_waitcnt lgkmcnt(0)
	s_barrier
	global_load_dwordx4 v[2:5], v1, s[18:19]
	global_load_dwordx4 v[6:9], v1, s[18:19] offset:112
	v_mov_b32_e32 v142, v181
	global_load_dwordx2 v[220:221], v1, s[18:19] offset:144
	global_load_dwordx4 v[222:225], v1, s[18:19] offset:160
	global_load_dwordx2 v[10:11], v1, s[18:19] offset:184
	s_waitcnt vmcnt(0)
	v_readfirstlane_b32 s3, v6
	v_readfirstlane_b32 s5, v7
	v_readfirstlane_b32 s48, v8
	v_readfirstlane_b32 s49, v9
	v_readfirstlane_b32 s27, v220
	v_readfirstlane_b32 s59, v221
	v_mov_b32_e32 v6, v222
	v_mov_b32_e32 v7, v223
	v_mov_b32_e32 v8, v224
	v_mov_b32_e32 v9, v225
	v_readlane_b32 s18, v253, 51
	v_readlane_b32 s19, v253, 52
	s_andn2_b64 vcc, exec, s[18:19]
	v_readfirstlane_b32 s1, v142
	v_cndmask_b32_e64 v0, 0, 1, s[18:19]
	v_cmp_ne_u32_e64 s[40:41], 1, v0
	s_waitcnt vmcnt(0)
	v_readfirstlane_b32 s24, v10
	v_readfirstlane_b32 s25, v11
	s_cbranch_vccnz .LBB0_459
	v_readlane_b32 s18, v253, 53
	v_readlane_b32 s19, v253, 54
	s_andn2_b64 vcc, exec, s[18:19]
	s_cbranch_vccnz .LBB0_462
	v_readlane_b32 s11, v254, 11
	s_mov_b32 s28, s11
	v_readlane_b32 s11, v254, 14
	s_mov_b32 s78, 32
	s_mov_b32 s79, 0
	s_mov_b32 s74, s11
	s_mov_b32 s30, 0
